# grid barrier: every workgroup issues an early non-blocking L2 write-back (buffer_wbl2 sc1) when it arrives, so the XCD leader's final write-back has less left to flush
# baseline (speedup 1.0000x reference)
; __device__ __forceinline__ unsigned xb_ld(unsigned* p)              { return __hip_atomic_load(p, __ATOMIC_RELAXED, __HIP_MEMORY_SCOPE_AGENT); }
; __device__ __forceinline__ unsigned xb_add(unsigned* p, unsigned v) { return __hip_atomic_fetch_add(p, v, __ATOMIC_RELAXED, __HIP_MEMORY_SCOPE_AGENT); }
; #define XB_SPIN(cond, bar) do { unsigned _sp = 0; while (cond) { __builtin_amdgcn_s_sleep(1); \
;     if ((++_sp & 255u) == 0u) { if (xb_ld(&(bar)[XB_TMO])) break; if (_sp > XB_SPIN_CAP) { atomicAdd(&(bar)[XB_TMO], 1u); break; } } } } while (0)
; __device__ __forceinline__ void xcd_barrier(const XcdBarrier& b) {
;     ...
;     if (threadIdx.x == 0) {
;         unsigned* bar = b.bar;
;         __builtin_amdgcn_s_waitcnt(0);
;         unsigned nloc = b.st[0], nx = b.st[1];
;         if (nloc == 0u) { xcd_barrier_complete(bar, b.x, nloc, nx); b.st[0] = nloc; b.st[1] = nx; }
;         const unsigned old = xb_add(&bar[XB_XSUB(b.x)], 1u);
;         const unsigned gen = old / nloc;
;         if (old + 1u == (gen + 1u) * nloc) {
;             __builtin_amdgcn_fence(__ATOMIC_RELEASE, "agent");
;             asm volatile("s_waitcnt vmcnt(0)" ::: "memory");
;             const unsigned og = xb_add(&bar[XB_TOP], 1u);
;             const unsigned tg = og / nx;
;             if (og + 1u == (tg + 1u) * nx) xb_add(&bar[XB_TOPGEN], 1u);
;             else XB_SPIN(xb_ld(&bar[XB_TOPGEN]) == tg, bar);
;             __builtin_amdgcn_fence(__ATOMIC_ACQUIRE, "agent");
;             xb_add(&bar[XB_XGEN(b.x)], 1u);
;             asm volatile("s_waitcnt vmcnt(0)" ::: "memory");
;         } else {
;             XB_SPIN(xb_ld(&bar[XB_XGEN(b.x)]) == gen, bar);
.LBB0_59:
	s_lshl_b32 s0, s33, 8
	s_add_u32 s23, s36, s0
	s_addc_u32 s22, s37, 0
	v_mov_b32_e32 v1, s23
	v_add_co_u32_e32 v4, vcc, 0x1000, v1
	v_mov_b32_e32 v1, s22
	s_nop 0
	v_addc_co_u32_e32 v5, vcc, 0, v1, vcc
	v_mov_b32_e32 v1, 1
	buffer_wbl2 sc1
	flat_atomic_add v1, v[4:5], v1 offset:1024 sc0
	v_cvt_f32_u32_e32 v3, v2
	v_sub_u32_e32 v4, 0, v2
	v_rcp_iflag_f32_e32 v3, v3
	s_nop 0
	v_mul_f32_e32 v3, 0x4f7ffffe, v3
	v_cvt_u32_f32_e32 v3, v3
	v_mul_lo_u32 v4, v4, v3
	v_mul_hi_u32 v4, v3, v4
	v_add_u32_e32 v3, v3, v4
	s_waitcnt vmcnt(0) lgkmcnt(0)
	v_mul_hi_u32 v3, v1, v3
	v_mul_lo_u32 v5, v3, v2
	v_add_u32_e32 v4, 1, v1
	v_sub_u32_e32 v1, v1, v5
	v_add_u32_e32 v6, 1, v3
	v_cmp_ge_u32_e32 vcc, v1, v2
	v_sub_u32_e32 v5, v1, v2
	s_nop 0
	v_cndmask_b32_e32 v3, v3, v6, vcc
	v_cndmask_b32_e32 v1, v1, v5, vcc
	v_add_u32_e32 v5, 1, v3
	v_cmp_ge_u32_e32 vcc, v1, v2
	s_nop 1
	v_cndmask_b32_e32 v1, v3, v5, vcc
	v_mad_u64_u32 v[2:3], s[0:1], v2, v1, v[2:3]
	v_cmp_ne_u32_e32 vcc, v4, v2
	s_and_saveexec_b64 s[0:1], vcc
	s_xor_b64 s[0:1], exec, s[0:1]
	s_cbranch_execz .LBB0_72
	v_mov_b32_e32 v0, s23
	v_add_co_u32_e32 v2, vcc, 0x2000, v0
	v_mov_b32_e32 v0, s22
	s_nop 0
	v_addc_co_u32_e32 v3, vcc, 0, v0, vcc
	flat_load_dword v0, v[2:3] offset:1024 sc1
	s_add_u32 s6, s23, 0x2400
	s_addc_u32 s7, s22, 0
	s_waitcnt vmcnt(0) lgkmcnt(0)
	v_cmp_eq_u32_e32 vcc, v0, v1
	s_and_saveexec_b64 s[4:5], vcc
	s_cbranch_execz .LBB0_71
	s_mov_b32 s24, 1
	s_mov_b64 s[8:9], 0
	s_branch .LBB0_63

; __device__ __forceinline__ unsigned xb_ld(unsigned* p)              { return __hip_atomic_load(p, __ATOMIC_RELAXED, __HIP_MEMORY_SCOPE_AGENT); }
; __device__ __forceinline__ unsigned xb_add(unsigned* p, unsigned v) { return __hip_atomic_fetch_add(p, v, __ATOMIC_RELAXED, __HIP_MEMORY_SCOPE_AGENT); }
; #define XB_SPIN(cond, bar) do { unsigned _sp = 0; while (cond) { __builtin_amdgcn_s_sleep(1); \
;     if ((++_sp & 255u) == 0u) { if (xb_ld(&(bar)[XB_TMO])) break; if (_sp > XB_SPIN_CAP) { atomicAdd(&(bar)[XB_TMO], 1u); break; } } } } while (0)
; __device__ __forceinline__ void xcd_barrier(const XcdBarrier& b) {
;     ...
;     if (threadIdx.x == 0) {
;         unsigned* bar = b.bar;
;         __builtin_amdgcn_s_waitcnt(0);
;         unsigned nloc = b.st[0], nx = b.st[1];
;         if (nloc == 0u) { xcd_barrier_complete(bar, b.x, nloc, nx); b.st[0] = nloc; b.st[1] = nx; }
;         const unsigned old = xb_add(&bar[XB_XSUB(b.x)], 1u);
;         const unsigned gen = old / nloc;
;         if (old + 1u == (gen + 1u) * nloc) {
;             __builtin_amdgcn_fence(__ATOMIC_RELEASE, "agent");
;             asm volatile("s_waitcnt vmcnt(0)" ::: "memory");
;             const unsigned og = xb_add(&bar[XB_TOP], 1u);
;             const unsigned tg = og / nx;
;             if (og + 1u == (tg + 1u) * nx) xb_add(&bar[XB_TOPGEN], 1u);
;             else XB_SPIN(xb_ld(&bar[XB_TOPGEN]) == tg, bar);
;             __builtin_amdgcn_fence(__ATOMIC_ACQUIRE, "agent");
;             xb_add(&bar[XB_XGEN(b.x)], 1u);
;             asm volatile("s_waitcnt vmcnt(0)" ::: "memory");
;         } else {
;             XB_SPIN(xb_ld(&bar[XB_XGEN(b.x)]) == gen, bar);
.LBB0_128:
	v_readlane_b32 s4, v254, 26
	s_lshl_b32 s4, s4, 2
	s_add_u32 s5, s20, s4
	s_addc_u32 s4, s21, 0
	v_mov_b32_e32 v5, s5
	v_add_co_u32_e32 v8, vcc, 0x1000, v5
	v_mov_b32_e32 v5, s4
	s_nop 0
	v_addc_co_u32_e32 v9, vcc, 0, v5, vcc
	buffer_wbl2 sc1
	flat_atomic_add v5, v[8:9], v252 offset:1024 sc0
	v_cvt_f32_u32_e32 v7, v6
	v_sub_u32_e32 v8, 0, v6
	v_rcp_iflag_f32_e32 v7, v7
	s_nop 0
	v_mul_f32_e32 v7, 0x4f7ffffe, v7
	v_cvt_u32_f32_e32 v7, v7
	v_mul_lo_u32 v8, v8, v7
	v_mul_hi_u32 v8, v7, v8
	v_add_u32_e32 v7, v7, v8
	s_waitcnt vmcnt(0) lgkmcnt(0)
	v_mul_hi_u32 v7, v5, v7
	v_mul_lo_u32 v9, v7, v6
	v_add_u32_e32 v8, 1, v5
	v_sub_u32_e32 v5, v5, v9
	v_add_u32_e32 v10, 1, v7
	v_cmp_ge_u32_e32 vcc, v5, v6
	v_sub_u32_e32 v9, v5, v6
	s_nop 0
	v_cndmask_b32_e32 v7, v7, v10, vcc
	v_cndmask_b32_e32 v5, v5, v9, vcc
	v_add_u32_e32 v9, 1, v7
	v_cmp_ge_u32_e32 vcc, v5, v6
	s_nop 1
	v_cndmask_b32_e32 v5, v7, v9, vcc
	v_mad_u64_u32 v[6:7], s[26:27], v6, v5, v[6:7]
	v_cmp_ne_u32_e32 vcc, v8, v6
	s_and_saveexec_b64 s[26:27], vcc
	s_xor_b64 s[26:27], exec, s[26:27]
	s_cbranch_execz .LBB0_141
	v_mov_b32_e32 v4, s5
	v_add_co_u32_e32 v6, vcc, 0x2000, v4
	v_mov_b32_e32 v4, s4
	s_nop 0
	v_addc_co_u32_e32 v7, vcc, 0, v4, vcc
	flat_load_dword v4, v[6:7] offset:1024 sc1
	s_add_u32 s36, s5, 0x2400
	s_addc_u32 s37, s4, 0
	s_waitcnt vmcnt(0) lgkmcnt(0)
	v_cmp_eq_u32_e32 vcc, v4, v5
	s_and_saveexec_b64 s[30:31], vcc
	s_cbranch_execz .LBB0_140
	s_mov_b32 s16, 1
	s_mov_b64 s[38:39], 0
	s_branch .LBB0_132

; __device__ __forceinline__ unsigned xb_ld(unsigned* p)              { return __hip_atomic_load(p, __ATOMIC_RELAXED, __HIP_MEMORY_SCOPE_AGENT); }
; __device__ __forceinline__ unsigned xb_add(unsigned* p, unsigned v) { return __hip_atomic_fetch_add(p, v, __ATOMIC_RELAXED, __HIP_MEMORY_SCOPE_AGENT); }
; #define XB_SPIN(cond, bar) do { unsigned _sp = 0; while (cond) { __builtin_amdgcn_s_sleep(1); \
;     if ((++_sp & 255u) == 0u) { if (xb_ld(&(bar)[XB_TMO])) break; if (_sp > XB_SPIN_CAP) { atomicAdd(&(bar)[XB_TMO], 1u); break; } } } } while (0)
; __device__ __forceinline__ void xcd_barrier(const XcdBarrier& b) {
;     ...
;     if (threadIdx.x == 0) {
;         unsigned* bar = b.bar;
;         __builtin_amdgcn_s_waitcnt(0);
;         unsigned nloc = b.st[0], nx = b.st[1];
;         if (nloc == 0u) { xcd_barrier_complete(bar, b.x, nloc, nx); b.st[0] = nloc; b.st[1] = nx; }
;         const unsigned old = xb_add(&bar[XB_XSUB(b.x)], 1u);
;         const unsigned gen = old / nloc;
;         if (old + 1u == (gen + 1u) * nloc) {
;             __builtin_amdgcn_fence(__ATOMIC_RELEASE, "agent");
;             asm volatile("s_waitcnt vmcnt(0)" ::: "memory");
;             const unsigned og = xb_add(&bar[XB_TOP], 1u);
;             const unsigned tg = og / nx;
;             if (og + 1u == (tg + 1u) * nx) xb_add(&bar[XB_TOPGEN], 1u);
;             else XB_SPIN(xb_ld(&bar[XB_TOPGEN]) == tg, bar);
;             __builtin_amdgcn_fence(__ATOMIC_ACQUIRE, "agent");
;             xb_add(&bar[XB_XGEN(b.x)], 1u);
;             asm volatile("s_waitcnt vmcnt(0)" ::: "memory");
;         } else {
;             XB_SPIN(xb_ld(&bar[XB_XGEN(b.x)]) == gen, bar);
.LBB0_218:
	v_readlane_b32 s4, v254, 26
	s_lshl_b32 s4, s4, 2
	s_add_u32 s5, s26, s4
	s_addc_u32 s4, s27, 0
	v_mov_b32_e32 v5, s5
	v_add_co_u32_e32 v8, vcc, 0x1000, v5
	v_mov_b32_e32 v5, s4
	s_nop 0
	v_addc_co_u32_e32 v9, vcc, 0, v5, vcc
	buffer_wbl2 sc1
	flat_atomic_add v7, v[8:9], v252 offset:1024 sc0
	v_cvt_f32_u32_e32 v5, v6
	v_sub_u32_e32 v8, 0, v6
	v_rcp_iflag_f32_e32 v5, v5
	s_nop 0
	v_mul_f32_e32 v5, 0x4f7ffffe, v5
	v_cvt_u32_f32_e32 v5, v5
	v_mul_lo_u32 v8, v8, v5
	v_mul_hi_u32 v8, v5, v8
	v_add_u32_e32 v5, v5, v8
	s_waitcnt vmcnt(0) lgkmcnt(0)
	v_mul_hi_u32 v5, v7, v5
	v_mul_lo_u32 v8, v5, v6
	v_sub_u32_e32 v8, v7, v8
	v_cmp_ge_u32_e32 vcc, v8, v6
	v_add_u32_e32 v9, 1, v5
	s_nop 0
	v_cndmask_b32_e32 v5, v5, v9, vcc
	v_sub_u32_e32 v9, v8, v6
	v_cndmask_b32_e32 v8, v8, v9, vcc
	v_cmp_ge_u32_e32 vcc, v8, v6
	v_add_u32_e32 v8, 1, v5
	s_nop 0
	v_cndmask_b32_e32 v5, v5, v8, vcc
	v_add_u32_e32 v8, 1, v7
	v_mad_u64_u32 v[6:7], s[30:31], v6, v5, v[6:7]
	v_cmp_ne_u32_e32 vcc, v8, v6
	s_and_saveexec_b64 s[30:31], vcc
	s_xor_b64 s[30:31], exec, s[30:31]
	s_cbranch_execz .LBB0_231
	v_mov_b32_e32 v4, s5
	v_add_co_u32_e32 v6, vcc, 0x2000, v4
	v_mov_b32_e32 v4, s4
	s_nop 0
	v_addc_co_u32_e32 v7, vcc, 0, v4, vcc
	flat_load_dword v4, v[6:7] offset:1024 sc1
	s_add_u32 s38, s5, 0x2400
	s_addc_u32 s39, s4, 0
	s_waitcnt vmcnt(0) lgkmcnt(0)
	v_cmp_eq_u32_e32 vcc, v4, v5
	s_and_saveexec_b64 s[36:37], vcc
	s_cbranch_execz .LBB0_230
	s_mov_b32 s16, 1
	s_mov_b64 s[40:41], 0
	s_branch .LBB0_222

; __device__ __forceinline__ unsigned xb_ld(unsigned* p)              { return __hip_atomic_load(p, __ATOMIC_RELAXED, __HIP_MEMORY_SCOPE_AGENT); }
; __device__ __forceinline__ unsigned xb_add(unsigned* p, unsigned v) { return __hip_atomic_fetch_add(p, v, __ATOMIC_RELAXED, __HIP_MEMORY_SCOPE_AGENT); }
; #define XB_SPIN(cond, bar) do { unsigned _sp = 0; while (cond) { __builtin_amdgcn_s_sleep(1); \
;     if ((++_sp & 255u) == 0u) { if (xb_ld(&(bar)[XB_TMO])) break; if (_sp > XB_SPIN_CAP) { atomicAdd(&(bar)[XB_TMO], 1u); break; } } } } while (0)
; __device__ __forceinline__ void xcd_barrier(const XcdBarrier& b) {
;     ...
;     if (threadIdx.x == 0) {
;         unsigned* bar = b.bar;
;         __builtin_amdgcn_s_waitcnt(0);
;         unsigned nloc = b.st[0], nx = b.st[1];
;         if (nloc == 0u) { xcd_barrier_complete(bar, b.x, nloc, nx); b.st[0] = nloc; b.st[1] = nx; }
;         const unsigned old = xb_add(&bar[XB_XSUB(b.x)], 1u);
;         const unsigned gen = old / nloc;
;         if (old + 1u == (gen + 1u) * nloc) {
;             __builtin_amdgcn_fence(__ATOMIC_RELEASE, "agent");
;             asm volatile("s_waitcnt vmcnt(0)" ::: "memory");
;             const unsigned og = xb_add(&bar[XB_TOP], 1u);
;             const unsigned tg = og / nx;
;             if (og + 1u == (tg + 1u) * nx) xb_add(&bar[XB_TOPGEN], 1u);
;             else XB_SPIN(xb_ld(&bar[XB_TOPGEN]) == tg, bar);
;             __builtin_amdgcn_fence(__ATOMIC_ACQUIRE, "agent");
;             xb_add(&bar[XB_XGEN(b.x)], 1u);
;             asm volatile("s_waitcnt vmcnt(0)" ::: "memory");
;         } else {
;             XB_SPIN(xb_ld(&bar[XB_XGEN(b.x)]) == gen, bar);
.LBB0_540:
	v_readlane_b32 s4, v254, 26
	s_lshl_b32 s4, s4, 2
	s_add_u32 s5, s20, s4
	s_addc_u32 s4, s21, 0
	v_mov_b32_e32 v5, s5
	v_add_co_u32_e32 v8, vcc, 0x1000, v5
	v_mov_b32_e32 v5, s4
	s_nop 0
	v_addc_co_u32_e32 v9, vcc, 0, v5, vcc
	buffer_wbl2 sc1
	flat_atomic_add v7, v[8:9], v252 offset:1024 sc0
	v_cvt_f32_u32_e32 v5, v6
	v_sub_u32_e32 v8, 0, v6
	v_rcp_iflag_f32_e32 v5, v5
	s_nop 0
	v_mul_f32_e32 v5, 0x4f7ffffe, v5
	v_cvt_u32_f32_e32 v5, v5
	v_mul_lo_u32 v8, v8, v5
	v_mul_hi_u32 v8, v5, v8
	v_add_u32_e32 v5, v5, v8
	s_waitcnt vmcnt(0) lgkmcnt(0)
	v_mul_hi_u32 v5, v7, v5
	v_mul_lo_u32 v8, v5, v6
	v_sub_u32_e32 v8, v7, v8
	v_cmp_ge_u32_e32 vcc, v8, v6
	v_add_u32_e32 v9, 1, v5
	s_nop 0
	v_cndmask_b32_e32 v5, v5, v9, vcc
	v_sub_u32_e32 v9, v8, v6
	v_cndmask_b32_e32 v8, v8, v9, vcc
	v_cmp_ge_u32_e32 vcc, v8, v6
	v_add_u32_e32 v8, 1, v5
	s_nop 0
	v_cndmask_b32_e32 v5, v5, v8, vcc
	v_add_u32_e32 v8, 1, v7
	v_mad_u64_u32 v[6:7], s[30:31], v6, v5, v[6:7]
	v_cmp_ne_u32_e32 vcc, v8, v6
	s_and_saveexec_b64 s[30:31], vcc
	s_xor_b64 s[30:31], exec, s[30:31]
	s_cbranch_execz .LBB0_553
	v_mov_b32_e32 v4, s5
	v_add_co_u32_e32 v6, vcc, 0x2000, v4
	v_mov_b32_e32 v4, s4
	s_nop 0
	v_addc_co_u32_e32 v7, vcc, 0, v4, vcc
	flat_load_dword v4, v[6:7] offset:1024 sc1
	s_add_u32 s38, s5, 0x2400
	s_addc_u32 s39, s4, 0
	s_waitcnt vmcnt(0) lgkmcnt(0)
	v_cmp_eq_u32_e32 vcc, v4, v5
	s_and_saveexec_b64 s[36:37], vcc
	s_cbranch_execz .LBB0_552
	s_mov_b32 s16, 1
	s_mov_b64 s[40:41], 0
	s_branch .LBB0_544

; __device__ __forceinline__ unsigned xb_ld(unsigned* p)              { return __hip_atomic_load(p, __ATOMIC_RELAXED, __HIP_MEMORY_SCOPE_AGENT); }
; __device__ __forceinline__ unsigned xb_add(unsigned* p, unsigned v) { return __hip_atomic_fetch_add(p, v, __ATOMIC_RELAXED, __HIP_MEMORY_SCOPE_AGENT); }
; #define XB_SPIN(cond, bar) do { unsigned _sp = 0; while (cond) { __builtin_amdgcn_s_sleep(1); \
;     if ((++_sp & 255u) == 0u) { if (xb_ld(&(bar)[XB_TMO])) break; if (_sp > XB_SPIN_CAP) { atomicAdd(&(bar)[XB_TMO], 1u); break; } } } } while (0)
; __device__ __forceinline__ void xcd_barrier(const XcdBarrier& b) {
;     ...
;     if (threadIdx.x == 0) {
;         unsigned* bar = b.bar;
;         __builtin_amdgcn_s_waitcnt(0);
;         unsigned nloc = b.st[0], nx = b.st[1];
;         if (nloc == 0u) { xcd_barrier_complete(bar, b.x, nloc, nx); b.st[0] = nloc; b.st[1] = nx; }
;         const unsigned old = xb_add(&bar[XB_XSUB(b.x)], 1u);
;         const unsigned gen = old / nloc;
;         if (old + 1u == (gen + 1u) * nloc) {
;             __builtin_amdgcn_fence(__ATOMIC_RELEASE, "agent");
;             asm volatile("s_waitcnt vmcnt(0)" ::: "memory");
;             const unsigned og = xb_add(&bar[XB_TOP], 1u);
;             const unsigned tg = og / nx;
;             if (og + 1u == (tg + 1u) * nx) xb_add(&bar[XB_TOPGEN], 1u);
;             else XB_SPIN(xb_ld(&bar[XB_TOPGEN]) == tg, bar);
;             __builtin_amdgcn_fence(__ATOMIC_ACQUIRE, "agent");
;             xb_add(&bar[XB_XGEN(b.x)], 1u);
;             asm volatile("s_waitcnt vmcnt(0)" ::: "memory");
;         } else {
;             XB_SPIN(xb_ld(&bar[XB_XGEN(b.x)]) == gen, bar);
.LBB0_717:
	v_readlane_b32 s2, v254, 26
	s_lshl_b32 s2, s2, 2
	s_add_u32 s4, s18, s2
	s_addc_u32 s2, s19, 0
	v_mov_b32_e32 v5, s4
	v_add_co_u32_e32 v8, vcc, 0x1000, v5
	v_mov_b32_e32 v5, s2
	s_nop 0
	v_addc_co_u32_e32 v9, vcc, 0, v5, vcc
	buffer_wbl2 sc1
	flat_atomic_add v7, v[8:9], v252 offset:1024 sc0
	v_cvt_f32_u32_e32 v5, v6
	v_sub_u32_e32 v8, 0, v6
	v_rcp_iflag_f32_e32 v5, v5
	s_nop 0
	v_mul_f32_e32 v5, 0x4f7ffffe, v5
	v_cvt_u32_f32_e32 v5, v5
	v_mul_lo_u32 v8, v8, v5
	v_mul_hi_u32 v8, v5, v8
	v_add_u32_e32 v5, v5, v8
	s_waitcnt vmcnt(0) lgkmcnt(0)
	v_mul_hi_u32 v5, v7, v5
	v_mul_lo_u32 v8, v5, v6
	v_sub_u32_e32 v8, v7, v8
	v_cmp_ge_u32_e32 vcc, v8, v6
	v_add_u32_e32 v9, 1, v5
	s_nop 0
	v_cndmask_b32_e32 v5, v5, v9, vcc
	v_sub_u32_e32 v9, v8, v6
	v_cndmask_b32_e32 v8, v8, v9, vcc
	v_cmp_ge_u32_e32 vcc, v8, v6
	v_add_u32_e32 v8, 1, v5
	s_nop 0
	v_cndmask_b32_e32 v5, v5, v8, vcc
	v_add_u32_e32 v8, 1, v7
	v_mad_u64_u32 v[6:7], s[20:21], v6, v5, v[6:7]
	v_cmp_ne_u32_e32 vcc, v8, v6
	s_and_saveexec_b64 s[20:21], vcc
	s_xor_b64 s[20:21], exec, s[20:21]
	s_cbranch_execz .LBB0_730
	v_mov_b32_e32 v4, s4
	v_add_co_u32_e32 v6, vcc, 0x2000, v4
	v_mov_b32_e32 v4, s2
	s_nop 0
	v_addc_co_u32_e32 v7, vcc, 0, v4, vcc
	flat_load_dword v4, v[6:7] offset:1024 sc1
	s_add_u32 s30, s4, 0x2400
	s_addc_u32 s31, s2, 0
	s_waitcnt vmcnt(0) lgkmcnt(0)
	v_cmp_eq_u32_e32 vcc, v4, v5
	s_and_saveexec_b64 s[26:27], vcc
	s_cbranch_execz .LBB0_729
	s_mov_b32 s5, 1
	s_mov_b64 s[36:37], 0
	s_branch .LBB0_721
